# attention k-tile loop hand-scheduled: QK/PV MFMAs software-pipelined with exp/row-sum/pack VALU inside one tile
# speedup vs baseline: 1.1977x; 1.0155x over previous
.LBB0_943:
	s_and_b32 s12, s5, 64
	s_mulk_i32 s12, 0x90
	v_add_u32_e32 v150, s12, v237
	ds_read_b128 v[200:203], v150
	ds_read_b128 v[204:207], v150 offset:64
	v_add_u32_e32 v151, s12, v238
	v_lshl_add_u64 v[102:103], v[144:145], 0, v[16:17]
	global_load_dwordx4 v[102:105], v[102:103], off
	v_lshl_add_u64 v[106:107], v[140:141], 0, v[16:17]
	global_load_dwordx4 v[106:109], v[106:107], off
	v_lshl_add_u64 v[110:111], v[142:143], 0, v[16:17]
	global_load_dwordx4 v[110:113], v[110:111], off
	v_lshl_add_u64 v[114:115], v[138:139], 0, v[16:17]
	global_load_dwordx4 v[114:117], v[114:115], off
	s_waitcnt vmcnt(4)
	s_add_i32 s5, s5, 64
	s_waitcnt lgkmcnt(1)
	v_mfma_f32_16x16x32_bf16 v[152:155], v[200:203], v[8:11], v[0:3]
	v_add_u32_e32 v248, 0x4800, v151
	v_mfma_f32_16x16x32_bf16 v[156:159], v[200:203], v[18:21], v[0:3]
	v_add_u32_e32 v249, 0x5000, v151
	v_mfma_f32_16x16x32_bf16 v[160:163], v[200:203], v[26:29], v[0:3]
	v_add_u32_e32 v250, 0x5800, v151
	v_mfma_f32_16x16x32_bf16 v[164:167], v[200:203], v[34:37], v[0:3]
	ds_read_b128 v[200:203], v150 offset:2304
	v_add_u32_e32 v251, 0x6000, v151
	s_waitcnt lgkmcnt(1)
	v_mfma_f32_16x16x32_bf16 v[152:155], v[204:207], v[4:7], v[152:155]
	v_lshl_add_u64 v[138:139], v[138:139], 0, s[66:67]
	v_mfma_f32_16x16x32_bf16 v[156:159], v[204:207], v[12:15], v[156:159]
	v_lshl_add_u64 v[140:141], v[140:141], 0, s[66:67]
	v_mfma_f32_16x16x32_bf16 v[160:163], v[204:207], v[22:25], v[160:163]
	v_lshl_add_u64 v[142:143], v[142:143], 0, s[68:69]
	v_mfma_f32_16x16x32_bf16 v[164:167], v[204:207], v[30:33], v[164:167]
	ds_read_b128 v[204:207], v150 offset:2368
	v_lshl_add_u64 v[144:145], v[144:145], 0, s[68:69]
	s_waitcnt lgkmcnt(1)
	v_mfma_f32_16x16x32_bf16 v[168:171], v[200:203], v[8:11], v[0:3]
	ds_read2_b64 v[212:215], v248 offset1:4
	ds_read2_b64 v[216:219], v249 offset0:32 offset1:36
	ds_read2_b64 v[220:223], v250 offset0:64 offset1:68
	ds_read2_b64 v[244:247], v251 offset0:96 offset1:100
	v_exp_f32_e32 v152, v152
	v_exp_f32_e32 v153, v153
	v_exp_f32_e32 v154, v154
	v_exp_f32_e32 v155, v155
	v_add_f32_e32 v151, v152, v153
	v_mfma_f32_16x16x32_bf16 v[172:175], v[200:203], v[18:21], v[0:3]
	v_cvt_pk_bf16_f32 v152, v152, v153
	v_cvt_pk_bf16_f32 v153, v154, v155
	v_add_f32_e32 v154, v154, v155
	v_add_f32_e32 v151, v151, v154
	v_add_f32_e32 v149, v149, v151
	v_mfma_f32_16x16x32_bf16 v[176:179], v[200:203], v[26:29], v[0:3]
	v_exp_f32_e32 v156, v156
	v_exp_f32_e32 v157, v157
	v_exp_f32_e32 v158, v158
	v_exp_f32_e32 v159, v159
	v_add_f32_e32 v151, v156, v157
	v_mfma_f32_16x16x32_bf16 v[180:183], v[200:203], v[34:37], v[0:3]
	ds_read_b128 v[200:203], v150 offset:4608
	v_cvt_pk_bf16_f32 v156, v156, v157
	v_cvt_pk_bf16_f32 v157, v158, v159
	v_add_f32_e32 v158, v158, v159
	v_add_f32_e32 v151, v151, v158
	v_add_f32_e32 v148, v148, v151
	s_waitcnt lgkmcnt(5)
	v_mfma_f32_16x16x32_bf16 v[168:171], v[204:207], v[4:7], v[168:171]
	v_exp_f32_e32 v160, v160
	v_exp_f32_e32 v161, v161
	v_exp_f32_e32 v162, v162
	v_exp_f32_e32 v163, v163
	v_add_f32_e32 v151, v160, v161
	v_mfma_f32_16x16x32_bf16 v[172:175], v[204:207], v[12:15], v[172:175]
	v_cvt_pk_bf16_f32 v160, v160, v161
	v_cvt_pk_bf16_f32 v161, v162, v163
	v_add_f32_e32 v162, v162, v163
	v_add_f32_e32 v151, v151, v162
	v_add_f32_e32 v147, v147, v151
	v_mfma_f32_16x16x32_bf16 v[176:179], v[204:207], v[22:25], v[176:179]
	v_exp_f32_e32 v164, v164
	v_exp_f32_e32 v165, v165
	v_exp_f32_e32 v166, v166
	v_exp_f32_e32 v167, v167
	v_add_f32_e32 v151, v164, v165
	v_mfma_f32_16x16x32_bf16 v[180:183], v[204:207], v[30:33], v[180:183]
	ds_read_b128 v[204:207], v150 offset:4672
	v_cvt_pk_bf16_f32 v164, v164, v165
	v_cvt_pk_bf16_f32 v165, v166, v167
	v_add_f32_e32 v166, v166, v167
	v_add_f32_e32 v151, v151, v166
	v_add_f32_e32 v146, v146, v151
	s_waitcnt lgkmcnt(1)
	v_mfma_f32_16x16x32_bf16 v[184:187], v[200:203], v[8:11], v[0:3]
	v_exp_f32_e32 v168, v168
	v_exp_f32_e32 v169, v169
	v_exp_f32_e32 v170, v170
	v_exp_f32_e32 v171, v171
	v_cvt_pk_bf16_f32 v154, v168, v169
	v_mfma_f32_16x16x32_bf16 v[188:191], v[200:203], v[18:21], v[0:3]
	v_cvt_pk_bf16_f32 v155, v170, v171
	v_add_f32_e32 v168, v168, v169
	v_add_f32_e32 v170, v170, v171
	v_add_f32_e32 v168, v168, v170
	v_add_f32_e32 v149, v149, v168
	v_mfma_f32_16x16x32_bf16 v[192:195], v[200:203], v[26:29], v[0:3]
	v_exp_f32_e32 v172, v172
	v_exp_f32_e32 v173, v173
	v_exp_f32_e32 v174, v174
	v_exp_f32_e32 v175, v175
	v_cvt_pk_bf16_f32 v158, v172, v173
	v_mfma_f32_16x16x32_bf16 v[196:199], v[200:203], v[34:37], v[0:3]
	ds_read_b128 v[200:203], v150 offset:6912
	v_cvt_pk_bf16_f32 v159, v174, v175
	v_add_f32_e32 v172, v172, v173
	v_add_f32_e32 v174, v174, v175
	v_add_f32_e32 v172, v172, v174
	v_add_f32_e32 v148, v148, v172
	s_waitcnt lgkmcnt(1)
	v_mfma_f32_16x16x32_bf16 v[184:187], v[204:207], v[4:7], v[184:187]
	v_exp_f32_e32 v176, v176
	v_exp_f32_e32 v177, v177
	v_exp_f32_e32 v178, v178
	v_exp_f32_e32 v179, v179
	v_cvt_pk_bf16_f32 v162, v176, v177
	v_mfma_f32_16x16x32_bf16 v[188:191], v[204:207], v[12:15], v[188:191]
	v_cvt_pk_bf16_f32 v163, v178, v179
	v_add_f32_e32 v176, v176, v177
	v_add_f32_e32 v178, v178, v179
	v_add_f32_e32 v176, v176, v178
	v_add_f32_e32 v147, v147, v176
	v_mfma_f32_16x16x32_bf16 v[192:195], v[204:207], v[22:25], v[192:195]
	v_exp_f32_e32 v180, v180
	v_exp_f32_e32 v181, v181
	v_exp_f32_e32 v182, v182
	v_exp_f32_e32 v183, v183
	v_cvt_pk_bf16_f32 v166, v180, v181
	v_mfma_f32_16x16x32_bf16 v[196:199], v[204:207], v[30:33], v[196:199]
	ds_read_b128 v[204:207], v150 offset:6976
	v_cvt_pk_bf16_f32 v167, v182, v183
	v_add_f32_e32 v180, v180, v181
	v_add_f32_e32 v182, v182, v183
	v_add_f32_e32 v180, v180, v182
	v_add_f32_e32 v146, v146, v180
	v_mfma_f32_16x16x32_bf16 v[98:101], v[212:215], v[152:155], v[98:101]
	v_exp_f32_e32 v184, v184
	v_exp_f32_e32 v185, v185
	s_waitcnt lgkmcnt(1)
	v_mfma_f32_16x16x32_bf16 v[168:171], v[200:203], v[8:11], v[0:3]
	v_exp_f32_e32 v186, v186
	v_exp_f32_e32 v187, v187
	v_add_f32_e32 v151, v184, v185
	v_mfma_f32_16x16x32_bf16 v[94:97], v[212:215], v[156:159], v[94:97]
	v_cvt_pk_bf16_f32 v184, v184, v185
	v_cvt_pk_bf16_f32 v185, v186, v187
	v_mfma_f32_16x16x32_bf16 v[172:175], v[200:203], v[18:21], v[0:3]
	v_add_f32_e32 v186, v186, v187
	v_add_f32_e32 v151, v151, v186
	v_add_f32_e32 v149, v149, v151
	v_mfma_f32_16x16x32_bf16 v[90:93], v[212:215], v[160:163], v[90:93]
	v_exp_f32_e32 v188, v188
	v_exp_f32_e32 v189, v189
	v_mfma_f32_16x16x32_bf16 v[176:179], v[200:203], v[26:29], v[0:3]
	v_exp_f32_e32 v190, v190
	v_exp_f32_e32 v191, v191
	v_add_f32_e32 v151, v188, v189
	v_mfma_f32_16x16x32_bf16 v[86:89], v[212:215], v[164:167], v[86:89]
	v_cvt_pk_bf16_f32 v188, v188, v189
	v_cvt_pk_bf16_f32 v189, v190, v191
	v_mfma_f32_16x16x32_bf16 v[180:183], v[200:203], v[34:37], v[0:3]
	v_add_f32_e32 v190, v190, v191
	v_add_f32_e32 v151, v151, v190
	v_add_f32_e32 v148, v148, v151
	v_mfma_f32_16x16x32_bf16 v[82:85], v[216:219], v[152:155], v[82:85]
	v_exp_f32_e32 v192, v192
	v_exp_f32_e32 v193, v193
	s_waitcnt lgkmcnt(0)
	v_mfma_f32_16x16x32_bf16 v[168:171], v[204:207], v[4:7], v[168:171]
	v_exp_f32_e32 v194, v194
	v_exp_f32_e32 v195, v195
	v_add_f32_e32 v151, v192, v193
	v_mfma_f32_16x16x32_bf16 v[78:81], v[216:219], v[156:159], v[78:81]
	v_cvt_pk_bf16_f32 v192, v192, v193
	v_cvt_pk_bf16_f32 v193, v194, v195
	v_mfma_f32_16x16x32_bf16 v[172:175], v[204:207], v[12:15], v[172:175]
	v_add_f32_e32 v194, v194, v195
	v_add_f32_e32 v151, v151, v194
	v_add_f32_e32 v147, v147, v151
	v_mfma_f32_16x16x32_bf16 v[74:77], v[216:219], v[160:163], v[74:77]
	v_exp_f32_e32 v196, v196
	v_exp_f32_e32 v197, v197
	v_mfma_f32_16x16x32_bf16 v[176:179], v[204:207], v[22:25], v[176:179]
	v_exp_f32_e32 v198, v198
	v_exp_f32_e32 v199, v199
	v_add_f32_e32 v151, v196, v197
	v_mfma_f32_16x16x32_bf16 v[70:73], v[216:219], v[164:167], v[70:73]
	v_cvt_pk_bf16_f32 v196, v196, v197
	v_cvt_pk_bf16_f32 v197, v198, v199
	v_mfma_f32_16x16x32_bf16 v[180:183], v[204:207], v[30:33], v[180:183]
	v_add_f32_e32 v198, v198, v199
	v_add_f32_e32 v151, v151, v198
	v_add_f32_e32 v146, v146, v151
	v_mfma_f32_16x16x32_bf16 v[66:69], v[220:223], v[152:155], v[66:69]
	ds_read2_b64 v[212:215], v248 offset0:8 offset1:12
	ds_read2_b64 v[216:219], v249 offset0:40 offset1:44
	v_exp_f32_e32 v168, v168
	v_exp_f32_e32 v169, v169
	v_exp_f32_e32 v170, v170
	v_exp_f32_e32 v171, v171
	v_cvt_pk_bf16_f32 v186, v168, v169
	v_mfma_f32_16x16x32_bf16 v[62:65], v[220:223], v[156:159], v[62:65]
	v_cvt_pk_bf16_f32 v187, v170, v171
	v_add_f32_e32 v168, v168, v169
	v_add_f32_e32 v170, v170, v171
	v_add_f32_e32 v168, v168, v170
	v_add_f32_e32 v149, v149, v168
	v_mfma_f32_16x16x32_bf16 v[58:61], v[220:223], v[160:163], v[58:61]
	v_exp_f32_e32 v172, v172
	v_exp_f32_e32 v173, v173
	v_exp_f32_e32 v174, v174
	v_exp_f32_e32 v175, v175
	v_cvt_pk_bf16_f32 v190, v172, v173
	v_mfma_f32_16x16x32_bf16 v[54:57], v[220:223], v[164:167], v[54:57]
	v_cvt_pk_bf16_f32 v191, v174, v175
	v_add_f32_e32 v172, v172, v173
	v_add_f32_e32 v174, v174, v175
	v_add_f32_e32 v172, v172, v174
	v_add_f32_e32 v148, v148, v172
	v_mfma_f32_16x16x32_bf16 v[50:53], v[244:247], v[152:155], v[50:53]
	v_exp_f32_e32 v176, v176
	v_exp_f32_e32 v177, v177
	v_exp_f32_e32 v178, v178
	v_exp_f32_e32 v179, v179
	v_cvt_pk_bf16_f32 v194, v176, v177
	v_mfma_f32_16x16x32_bf16 v[46:49], v[244:247], v[156:159], v[46:49]
	v_cvt_pk_bf16_f32 v195, v178, v179
	v_add_f32_e32 v176, v176, v177
	v_add_f32_e32 v178, v178, v179
	v_add_f32_e32 v176, v176, v178
	v_add_f32_e32 v147, v147, v176
	v_mfma_f32_16x16x32_bf16 v[42:45], v[244:247], v[160:163], v[42:45]
	v_exp_f32_e32 v180, v180
	v_exp_f32_e32 v181, v181
	v_exp_f32_e32 v182, v182
	v_exp_f32_e32 v183, v183
	v_cvt_pk_bf16_f32 v198, v180, v181
	v_mfma_f32_16x16x32_bf16 v[38:41], v[244:247], v[164:167], v[38:41]
	v_cvt_pk_bf16_f32 v199, v182, v183
	v_add_f32_e32 v180, v180, v181
	v_add_f32_e32 v182, v182, v183
	v_add_f32_e32 v180, v180, v182
	v_add_f32_e32 v146, v146, v180
	ds_read2_b64 v[220:223], v250 offset0:72 offset1:76
	ds_read2_b64 v[244:247], v251 offset0:104 offset1:108
	s_waitcnt lgkmcnt(3)
	v_mfma_f32_16x16x32_bf16 v[98:101], v[212:215], v[184:187], v[98:101]
	v_mfma_f32_16x16x32_bf16 v[94:97], v[212:215], v[188:191], v[94:97]
	v_mfma_f32_16x16x32_bf16 v[90:93], v[212:215], v[192:195], v[90:93]
	v_mfma_f32_16x16x32_bf16 v[86:89], v[212:215], v[196:199], v[86:89]
	s_waitcnt lgkmcnt(2)
	v_mfma_f32_16x16x32_bf16 v[82:85], v[216:219], v[184:187], v[82:85]
	v_mfma_f32_16x16x32_bf16 v[78:81], v[216:219], v[188:191], v[78:81]
	v_mfma_f32_16x16x32_bf16 v[74:77], v[216:219], v[192:195], v[74:77]
	v_mfma_f32_16x16x32_bf16 v[70:73], v[216:219], v[196:199], v[70:73]
	s_waitcnt lgkmcnt(1)
	v_mfma_f32_16x16x32_bf16 v[66:69], v[220:223], v[184:187], v[66:69]
	s_and_b32 s12, s5, 64
	v_mfma_f32_16x16x32_bf16 v[62:65], v[220:223], v[188:191], v[62:65]
	s_mulk_i32 s12, 0x90
	v_add_u32_e32 v200, s12, v230
	v_mfma_f32_16x16x32_bf16 v[58:61], v[220:223], v[192:195], v[58:61]
	v_lshl_add_u32 v201, v233, 1, v200
	v_mfma_f32_16x16x32_bf16 v[54:57], v[220:223], v[196:199], v[54:57]
	v_lshl_add_u32 v202, v235, 1, v200
	s_waitcnt vmcnt(3)
	s_waitcnt lgkmcnt(0)
	v_mfma_f32_16x16x32_bf16 v[50:53], v[244:247], v[184:187], v[50:53]
	ds_write_b128 v201, v[102:105]
	s_waitcnt vmcnt(2)
	v_mfma_f32_16x16x32_bf16 v[46:49], v[244:247], v[188:191], v[46:49]
	ds_write_b128 v201, v[106:109] offset:18432
	v_mfma_f32_16x16x32_bf16 v[42:45], v[244:247], v[192:195], v[42:45]
	s_waitcnt vmcnt(1)
	ds_write_b128 v202, v[110:113]
	v_mfma_f32_16x16x32_bf16 v[38:41], v[244:247], v[196:199], v[38:41]
	s_waitcnt vmcnt(0)
	ds_write_b128 v202, v[114:117] offset:18432
	s_cmp_eq_u32 s11, s5
	s_waitcnt lgkmcnt(0)
	s_barrier
	s_cbranch_scc0 .LBB0_943
	ds_read_b128 v[102:105], v237 offset:9216
	ds_read_b128 v[106:109], v237 offset:9280
	ds_read_b128 v[186:189], v237 offset:11520
	ds_read_b128 v[196:199], v237 offset:11584
	ds_read_b128 v[244:247], v237 offset:13824
	ds_read_b128 v[248:251], v237 offset:13888
	ds_read_b128 v[216:219], v237 offset:16128
	ds_read_b128 v[220:223], v237 offset:16192
	s_waitcnt lgkmcnt(7)
	v_mfma_f32_16x16x32_bf16 v[110:113], v[102:105], v[8:11], v[0:3]
	s_lshl_b32 s52, s4, 1
	s_add_i32 s6, s6, s3
	s_cmpk_gt_i32 s6, 0x40f
	v_mfma_f32_16x16x32_bf16 v[114:117], v[102:105], v[18:21], v[0:3]
	v_mfma_f32_16x16x32_bf16 v[164:167], v[102:105], v[26:29], v[0:3]
	v_mfma_f32_16x16x32_bf16 v[102:105], v[102:105], v[34:37], v[0:3]
	s_waitcnt lgkmcnt(6)
	v_mfma_f32_16x16x32_bf16 v[110:113], v[106:109], v[4:7], v[110:113]
	v_mfma_f32_16x16x32_bf16 v[114:117], v[106:109], v[12:15], v[114:117]
	s_waitcnt lgkmcnt(5)
	v_mfma_f32_16x16x32_bf16 v[152:155], v[186:189], v[18:21], v[0:3]
	s_nop 4
	v_exp_f32_e32 v140, v110
	v_exp_f32_e32 v150, v111
	v_exp_f32_e32 v156, v112
	v_exp_f32_e32 v162, v113
	s_waitcnt lgkmcnt(4)
	v_mfma_f32_16x16x32_bf16 v[110:113], v[196:199], v[12:15], v[152:155]
	v_exp_f32_e32 v168, v116
	v_exp_f32_e32 v176, v117
	s_nop 0
	v_exp_f32_e32 v154, v114
	v_mfma_f32_16x16x32_bf16 v[178:181], v[106:109], v[22:25], v[164:167]
	s_nop 2
	v_exp_f32_e32 v152, v110
	v_exp_f32_e32 v160, v111
	v_exp_f32_e32 v172, v113
	v_exp_f32_e32 v166, v115
	v_mfma_f32_16x16x32_bf16 v[102:105], v[106:109], v[30:33], v[102:105]
	v_exp_f32_e32 v164, v112
	v_exp_f32_e32 v174, v178
	v_exp_f32_e32 v194, v181
	v_mfma_f32_16x16x32_bf16 v[106:109], v[186:189], v[34:37], v[0:3]
	s_waitcnt lgkmcnt(3)
	v_mfma_f32_16x16x32_bf16 v[114:117], v[244:247], v[34:37], v[0:3]
	s_nop 1
	v_exp_f32_e32 v190, v102
	v_exp_f32_e32 v200, v103
	v_exp_f32_e32 v204, v105
	s_waitcnt lgkmcnt(1)
	v_mfma_f32_16x16x32_bf16 v[34:37], v[216:219], v[34:37], v[0:3]
	v_cvt_pk_bf16_f32 v102, v140, v150
	v_cvt_pk_bf16_f32 v103, v156, v162
	v_mfma_f32_16x16x32_bf16 v[142:145], v[186:189], v[8:11], v[0:3]
	v_mfma_f32_16x16x32_bf16 v[182:185], v[186:189], v[26:29], v[0:3]
	v_mfma_f32_16x16x32_bf16 v[106:109], v[196:199], v[30:33], v[106:109]
	v_mfma_f32_16x16x32_bf16 v[212:215], v[248:251], v[30:33], v[114:117]
	v_cvt_pk_bf16_f32 v114, v190, v200
	s_nop 6
	v_exp_f32_e32 v186, v106
	v_exp_f32_e32 v192, v107
	s_waitcnt lgkmcnt(0)
	v_mfma_f32_16x16x32_bf16 v[30:33], v[220:223], v[30:33], v[34:37]
	v_exp_f32_e32 v202, v109
	v_exp_f32_e32 v191, v212
	v_exp_f32_e32 v201, v213
	v_mfma_f32_16x16x32_bf16 v[34:37], v[244:247], v[26:29], v[0:3]
	v_exp_f32_e32 v205, v215
	s_nop 2
	v_exp_f32_e32 v187, v30
	v_exp_f32_e32 v193, v31
	v_mfma_f32_16x16x32_bf16 v[26:29], v[216:219], v[26:29], v[0:3]
	v_exp_f32_e32 v203, v33
	v_cvt_pk_bf16_f32 v106, v154, v166
	v_cvt_pk_bf16_f32 v107, v168, v176
	v_mfma_f32_16x16x32_bf16 v[142:145], v[196:199], v[4:7], v[142:145]
	v_cvt_pk_bf16_f32 v109, v164, v172
	v_cvt_pk_bf16_f32 v116, v186, v192
	v_mfma_f32_16x16x32_bf16 v[110:113], v[196:199], v[22:25], v[182:185]
	v_exp_f32_e32 v197, v32
	v_exp_f32_e32 v198, v104
	v_exp_f32_e32 v199, v214
	v_mfma_f32_16x16x32_bf16 v[30:33], v[248:251], v[22:25], v[34:37]
	v_exp_f32_e32 v182, v179
	s_nop 2
	v_exp_f32_e32 v170, v110
	v_exp_f32_e32 v178, v111
	v_mfma_f32_16x16x32_bf16 v[22:25], v[220:223], v[22:25], v[26:29]
	v_exp_f32_e32 v184, v180
	v_exp_f32_e32 v180, v112
	v_exp_f32_e32 v188, v113
	v_exp_f32_e32 v175, v30
	v_mfma_f32_16x16x32_bf16 v[26:29], v[244:247], v[18:21], v[0:3]
	s_nop 2
	v_exp_f32_e32 v171, v22
	v_exp_f32_e32 v183, v31
	v_exp_f32_e32 v179, v23
	v_exp_f32_e32 v185, v32
	v_exp_f32_e32 v181, v24
	v_exp_f32_e32 v195, v33
	v_exp_f32_e32 v189, v25
	v_mfma_f32_16x16x32_bf16 v[18:21], v[216:219], v[18:21], v[0:3]
	v_add_f32_e64 v22, v174, v182
	v_add_f32_e64 v23, v175, v183
	v_add_f32_e32 v24, v184, v194
	v_add_f32_e32 v25, v185, v195
	v_cvt_pk_bf16_f32 v112, v170, v178
	v_mfma_f32_16x16x32_bf16 v[28:31], v[248:251], v[12:15], v[26:29]
	v_add_f32_e64 v22, v22, v24
	v_add_f32_e64 v23, v23, v25
	v_exp_f32_e32 v196, v108
	v_add_f32_e32 v34, v190, v200
	v_add_f32_e32 v35, v191, v201
	v_mfma_f32_16x16x32_bf16 v[12:15], v[220:223], v[12:15], v[18:21]
	v_add_f32_e64 v36, v198, v204
	v_add_f32_e64 v37, v199, v205
	v_add_f32_e32 v206, v196, v202
	v_add_f32_e32 v207, v197, v203
	v_add_f32_e32 v34, v34, v36
	v_add_f32_e32 v35, v35, v37
	v_add_f32_e32 v18, v170, v178
	v_add_f32_e32 v19, v171, v179
	v_add_f32_e32 v20, v180, v188
	v_add_f32_e32 v21, v181, v189
	v_add_u32_e32 v170, 0x6800, v238
	v_add_f32_e32 v24, v18, v20
	v_add_f32_e32 v25, v19, v21
	v_mfma_f32_16x16x32_bf16 v[18:21], v[244:247], v[8:11], v[0:3]
	v_add_f32_e64 v26, v22, v24
	v_add_f32_e64 v27, v23, v25
	ds_read2_b64 v[22:25], v170 offset0:128 offset1:132
	v_add_f32_e32 v36, v186, v192
	v_add_f32_e32 v37, v187, v193
	v_mfma_f32_16x16x32_bf16 v[8:11], v[216:219], v[8:11], v[0:3]
	v_exp_f32_e32 v138, v142
	v_exp_f32_e32 v142, v143
	v_exp_f32_e32 v144, v144
	v_mfma_f32_16x16x32_bf16 v[18:21], v[248:251], v[4:7], v[18:21]
	v_exp_f32_e32 v158, v145
	v_cvt_pk_bf16_f32 v104, v138, v142
	v_cvt_pk_bf16_f32 v105, v144, v158
	v_mfma_f32_16x16x32_bf16 v[4:7], v[220:223], v[4:7], v[8:11]
	v_add_f32_e64 v36, v36, v206
	v_add_f32_e64 v37, v37, v207
	v_exp_f32_e32 v169, v30
	v_exp_f32_e32 v177, v31
	s_waitcnt lgkmcnt(0)
	v_mfma_f32_16x16x32_bf16 v[30:33], v[22:25], v[102:105], v[98:101]
	v_exp_f32_e32 v141, v18
	v_add_u32_e32 v18, 0x7800, v238
	v_cvt_pk_bf16_f32 v108, v152, v160
	v_add_f32_e32 v206, v34, v36
	v_add_f32_e32 v207, v35, v37
	v_add_u32_e32 v98, 0x7000, v238
	v_mfma_f32_16x16x32_bf16 v[34:37], v[22:25], v[106:109], v[94:97]
	v_exp_f32_e32 v139, v4
	v_exp_f32_e32 v143, v5
	v_exp_f32_e32 v145, v6
	ds_read2_b64 v[94:97], v98 offset0:160 offset1:164
	v_exp_f32_e32 v159, v7
	ds_read2_b64 v[4:7], v18 offset0:192 offset1:196
	v_exp_f32_e32 v155, v28
	v_exp_f32_e32 v167, v29
	v_exp_f32_e32 v153, v12
	v_exp_f32_e32 v161, v13
	v_exp_f32_e32 v165, v14
	v_exp_f32_e32 v173, v15
	v_add_f32_e32 v8, v154, v166
	v_add_f32_e32 v9, v155, v167
	v_add_f32_e32 v10, v168, v176
	v_add_f32_e32 v11, v169, v177
	v_cvt_pk_bf16_f32 v110, v174, v182
	v_add_f32_e32 v12, v164, v172
	v_add_f32_e32 v13, v165, v173
	v_add_f32_e32 v8, v8, v10
	v_add_f32_e32 v9, v9, v11
	v_add_f32_e32 v10, v152, v160
	v_add_f32_e32 v11, v153, v161
	v_cvt_pk_bf16_f32 v111, v184, v194
	v_cvt_pk_bf16_f32 v113, v180, v188
	v_cvt_pk_bf16_f32 v115, v198, v204
	v_cvt_pk_bf16_f32 v117, v196, v202
	s_waitcnt lgkmcnt(1)
	v_mfma_f32_16x16x32_bf16 v[82:85], v[94:97], v[102:105], v[82:85]
	v_add_f32_e64 v10, v10, v12
	v_add_f32_e64 v11, v11, v13
	v_exp_f32_e32 v151, v19
	v_add_f32_e32 v28, v8, v10
	v_add_f32_e32 v29, v9, v11
	v_mfma_f32_16x16x32_bf16 v[90:93], v[22:25], v[110:113], v[90:93]
	v_add_u32_e32 v19, 0x8000, v238
	v_exp_f32_e32 v157, v20
	v_exp_f32_e32 v163, v21
	v_mfma_f32_16x16x32_bf16 v[86:89], v[22:25], v[114:117], v[86:89]
	v_add_f32_e64 v220, v140, v150
	v_add_f32_e64 v221, v141, v151
	v_add_f32_e32 v28, v148, v28
	v_add_f32_e32 v222, v156, v162
	v_add_f32_e32 v223, v157, v163
	v_mfma_f32_16x16x32_bf16 v[8:11], v[94:97], v[106:109], v[78:81]
	v_cvt_pk_bf16_f32 v148, v175, v183
	v_cvt_pk_bf16_f32 v150, v171, v179
	v_cvt_pk_bf16_f32 v152, v191, v201
	v_mfma_f32_16x16x32_bf16 v[12:15], v[94:97], v[110:113], v[74:77]
	v_cvt_pk_bf16_f32 v154, v187, v193
	v_mfma_f32_16x16x32_bf16 v[22:25], v[94:97], v[114:117], v[70:73]
	s_nop 2
	ds_read2_b64 v[70:73], v19 offset0:224 offset1:228
	ds_read2_b64 v[74:77], v170 offset0:136 offset1:140
	ds_read2_b64 v[78:81], v98 offset0:168 offset1:172
	ds_read2_b64 v[98:101], v18 offset0:200 offset1:204
	ds_read2_b64 v[18:21], v19 offset0:232 offset1:236
	s_waitcnt lgkmcnt(0)
	v_mfma_f32_16x16x32_bf16 v[94:97], v[4:7], v[102:105], v[66:69]
	s_barrier
	s_nop 1
	v_lshl_add_u64 v[66:67], v[128:129], 0, s[52:53]
	v_lshl_add_u64 v[68:69], v[66:67], 0, v[136:137]
	global_load_dwordx2 v[244:245], v[68:69], off
	v_mfma_f32_16x16x32_bf16 v[212:215], v[4:7], v[106:109], v[62:65]
	v_cvt_pk_bf16_f32 v136, v141, v151
	v_cvt_pk_bf16_f32 v137, v157, v163
	v_cvt_pk_bf16_f32 v151, v181, v189
	v_mfma_f32_16x16x32_bf16 v[216:219], v[4:7], v[110:113], v[58:61]
	v_mfma_f32_16x16x32_bf16 v[54:57], v[4:7], v[114:117], v[54:57]
	v_add_f32_e64 v6, v138, v142
	v_add_f32_e64 v7, v139, v143
	v_add_f32_e32 v58, v144, v158
	v_add_f32_e32 v59, v145, v159
	v_add_f32_e32 v4, v220, v222
	v_add_f32_e32 v5, v221, v223
	v_add_f32_e32 v6, v6, v58
	v_add_f32_e32 v7, v7, v59
	v_mfma_f32_16x16x32_bf16 v[106:109], v[70:73], v[106:109], v[46:49]
	v_add_f32_e64 v4, v4, v6
	v_add_f32_e64 v5, v5, v7
	v_cvt_pk_bf16_f32 v138, v139, v143
	v_cvt_pk_bf16_f32 v139, v145, v159
	v_mfma_f32_16x16x32_bf16 v[114:117], v[70:73], v[114:117], v[38:41]
	v_add_f32_e32 v4, v149, v4
	v_add_f32_e32 v58, v4, v5
	v_cvt_pk_bf16_f32 v38, v155, v167
	v_cvt_pk_bf16_f32 v39, v169, v177
	v_cvt_pk_bf16_f32 v40, v153, v161
	v_mfma_f32_16x16x32_bf16 v[140:143], v[74:77], v[136:139], v[30:33]
	v_cvt_pk_bf16_f32 v41, v165, v173
	v_cvt_pk_bf16_f32 v149, v185, v195
	v_cvt_pk_bf16_f32 v153, v199, v205
	v_cvt_pk_bf16_f32 v155, v197, v203
	v_mfma_f32_16x16x32_bf16 v[110:113], v[70:73], v[110:113], v[42:45]
	v_mfma_f32_16x16x32_bf16 v[46:49], v[74:77], v[38:41], v[34:37]
	v_mfma_f32_16x16x32_bf16 v[30:33], v[74:77], v[148:151], v[90:93]
	s_nop 1
	v_and_b32_e32 v35, 64, v209
	v_xor_b32_e32 v34, 16, v209
	v_add_u32_e32 v42, 64, v35
	v_mfma_f32_16x16x32_bf16 v[4:7], v[74:77], v[152:155], v[86:89]
	global_load_dwordx2 v[76:77], v[68:69], off offset:32
	v_cmp_lt_i32_e32 vcc, v34, v42
	v_mfma_f32_16x16x32_bf16 v[102:105], v[70:73], v[102:105], v[50:53]
	s_nop 0
	v_cndmask_b32_e32 v34, v209, v34, vcc
	v_lshlrev_b32_e32 v72, 2, v34
	v_add_f32_e32 v88, v28, v29
	v_mfma_f32_16x16x32_bf16 v[50:53], v[78:81], v[38:41], v[8:11]
	s_nop 2
	ds_bpermute_b32 v9, v72, v58
	v_xor_b32_e32 v8, 32, v209
	v_cmp_lt_i32_e32 vcc, v8, v42
	v_mfma_f32_16x16x32_bf16 v[62:65], v[78:81], v[136:139], v[82:85]
	v_add_f32_e32 v10, v147, v26
	v_cndmask_b32_e32 v8, v209, v8, vcc
	v_lshlrev_b32_e32 v73, 2, v8
	v_mfma_f32_16x16x32_bf16 v[34:37], v[78:81], v[148:151], v[12:15]
	s_waitcnt lgkmcnt(0)
	v_add_f32_e32 v8, v58, v9
	ds_bpermute_b32 v9, v73, v8
	v_add_f32_e32 v75, v10, v27
	v_mfma_f32_16x16x32_bf16 v[12:15], v[78:81], v[152:155], v[22:25]
	global_load_dwordx2 v[78:79], v[68:69], off offset:64
	global_load_dwordx2 v[80:81], v[68:69], off offset:96
	s_waitcnt lgkmcnt(0)
	v_add_f32_e32 v70, v8, v9
	v_div_scale_f32 v22, s[4:5], v70, v70, 1.0
	v_rcp_f32_e32 v23, v22
	v_add_f32_e32 v8, v146, v206
	v_add_f32_e32 v74, v8, v207
	v_div_scale_f32 v24, vcc, 1.0, v70, 1.0
	v_fma_f32 v8, -v22, v23, 1.0
	v_fmac_f32_e32 v23, v8, v23
	v_mul_f32_e32 v25, v24, v23
	v_fma_f32 v71, -v22, v25, v24
	v_fmac_f32_e32 v25, v71, v23
	v_fma_f32 v22, -v22, v25, v24
	v_div_fmas_f32 v71, v22, v23, v25
	v_div_fixup_f32 v70, v71, v70, 1.0
	s_waitcnt vmcnt(3)
	v_lshlrev_b32_e32 v71, 16, v244
	v_mul_f32_e32 v82, 0xbfb8aa3b, v71
	v_exp_f32_e32 v82, v82
	v_and_b32_e32 v84, 0xffff0000, v244
	v_lshlrev_b32_e32 v86, 16, v245
	v_and_b32_e32 v89, 0xffff0000, v245
	v_add_f32_e32 v82, 1.0, v82
	v_rcp_f32_e32 v83, v82
	v_mul_f32_e32 v82, 0xbfb8aa3b, v84
	v_exp_f32_e32 v85, v82
	v_mov_b32_e32 v82, v140
	v_pk_mul_f32 v[82:83], v[82:83], v[70:71]
	v_mfma_f32_16x16x32_bf16 v[58:61], v[98:101], v[136:139], v[94:97]
	v_add_f32_e32 v71, 1.0, v85
	v_mul_f32_e32 v87, v82, v83
	v_rcp_f32_e32 v83, v71
	v_mov_b32_e32 v71, v84
	v_mul_f32_e32 v84, 0xbfb8aa3b, v86
	v_exp_f32_e32 v84, v84
	v_mov_b32_e32 v82, v141
	v_pk_mul_f32 v[82:83], v[82:83], v[70:71]
	v_mfma_f32_16x16x32_bf16 v[8:11], v[98:101], v[152:155], v[54:57]
	v_mul_f32_e32 v71, v82, v83
	v_cvt_pk_bf16_f32 v82, v87, v71
	v_add_f32_e32 v71, 1.0, v84
	v_rcp_f32_e32 v85, v71
	v_mul_f32_e32 v71, 0xbfb8aa3b, v89
	v_exp_f32_e32 v83, v71
	v_mov_b32_e32 v84, v142
	v_mov_b32_e32 v71, v86
	v_pk_mul_f32 v[84:85], v[84:85], v[70:71]
	v_add_f32_e32 v71, 1.0, v83
	v_rcp_f32_e32 v87, v71
	v_mov_b32_e32 v86, v143
	v_mov_b32_e32 v71, v89
	v_mul_f32_e32 v83, v84, v85
	v_pk_mul_f32 v[84:85], v[86:87], v[70:71]
	v_mfma_f32_16x16x32_bf16 v[54:57], v[18:21], v[136:139], v[102:105]
	v_mul_f32_e32 v71, v84, v85
	v_cvt_pk_bf16_f32 v83, v83, v71
	s_waitcnt vmcnt(2)
	v_lshlrev_b32_e32 v71, 16, v76
	global_store_dwordx2 v[68:69], v[82:83], off
	v_mul_f32_e32 v82, 0xbfb8aa3b, v71
	v_exp_f32_e32 v82, v82
	v_and_b32_e32 v83, 0xffff0000, v76
	v_lshlrev_b32_e32 v84, 16, v77
	v_and_b32_e32 v85, 0xffff0000, v77
	v_add_f32_e32 v76, 1.0, v82
	v_rcp_f32_e32 v77, v76
	v_mul_f32_e32 v76, 0xbfb8aa3b, v83
	v_exp_f32_e32 v82, v76
	v_mov_b32_e32 v76, v62
	v_pk_mul_f32 v[76:77], v[76:77], v[70:71]
	v_mov_b32_e32 v71, v83
	v_add_f32_e32 v62, 1.0, v82
	v_mul_f32_e32 v86, v76, v77
	v_rcp_f32_e32 v77, v62
	v_mul_f32_e32 v62, 0xbfb8aa3b, v84
	v_exp_f32_e32 v82, v62
	v_mov_b32_e32 v76, v63
	v_pk_mul_f32 v[62:63], v[76:77], v[70:71]
	v_mov_b32_e32 v76, v64
	v_mul_f32_e32 v62, v62, v63
	v_add_f32_e32 v63, 1.0, v82
	v_rcp_f32_e32 v77, v63
	v_mul_f32_e32 v63, 0xbfb8aa3b, v85
	v_exp_f32_e32 v63, v63
	v_mov_b32_e32 v71, v84
	v_pk_mul_f32 v[76:77], v[76:77], v[70:71]
	v_mov_b32_e32 v82, v65
	v_add_f32_e32 v63, 1.0, v63
	v_rcp_f32_e32 v83, v63
	v_mov_b32_e32 v71, v85
	v_cvt_pk_bf16_f32 v62, v86, v62
	v_mul_f32_e32 v63, v76, v77
	v_pk_mul_f32 v[64:65], v[82:83], v[70:71]
	s_waitcnt vmcnt(2)
	v_lshlrev_b32_e32 v71, 16, v78
	v_mul_f32_e32 v64, v64, v65
	v_cvt_pk_bf16_f32 v63, v63, v64
	global_store_dwordx2 v[68:69], v[62:63], off offset:32
	v_mul_f32_e32 v62, 0xbfb8aa3b, v71
	v_exp_f32_e32 v62, v62
	v_and_b32_e32 v64, 0xffff0000, v78
	v_lshlrev_b32_e32 v78, 16, v79
	v_mul_f32_e32 v77, 0xbfb8aa3b, v78
	v_add_f32_e32 v62, 1.0, v62
	v_rcp_f32_e32 v63, v62
	v_mul_f32_e32 v62, 0xbfb8aa3b, v64
	v_exp_f32_e32 v65, v62
	v_mov_b32_e32 v62, v58
	v_pk_mul_f32 v[62:63], v[62:63], v[70:71]
	v_mov_b32_e32 v71, v64
	v_add_f32_e32 v58, 1.0, v65
	v_mul_f32_e32 v76, v62, v63
	v_rcp_f32_e32 v63, v58
	v_mov_b32_e32 v62, v59
	v_lshl_add_u64 v[58:59], v[66:67], 0, v[134:135]
	global_load_dwordx2 v[64:65], v[58:59], off
	v_exp_f32_e32 v77, v77
	v_pk_mul_f32 v[62:63], v[62:63], v[70:71]
	v_and_b32_e32 v82, 0xffff0000, v79
	v_mul_f32_e32 v62, v62, v63
	v_add_f32_e32 v63, 1.0, v77
	v_rcp_f32_e32 v77, v63
	v_mul_f32_e32 v63, 0xbfb8aa3b, v82
	v_exp_f32_e32 v63, v63
	v_cvt_pk_bf16_f32 v62, v76, v62
	v_mov_b32_e32 v76, v60
	v_mov_b32_e32 v71, v78
	v_add_f32_e32 v60, 1.0, v63
	v_rcp_f32_e32 v79, v60
	v_pk_mul_f32 v[76:77], v[76:77], v[70:71]
	v_mov_b32_e32 v78, v61
	v_mov_b32_e32 v71, v82
	v_pk_mul_f32 v[60:61], v[78:79], v[70:71]
	v_mul_f32_e32 v63, v76, v77
	v_mul_f32_e32 v60, v60, v61
	s_waitcnt vmcnt(3)
	v_lshlrev_b32_e32 v71, 16, v80
	v_cvt_pk_bf16_f32 v63, v63, v60
	v_mul_f32_e32 v60, 0xbfb8aa3b, v71
	v_exp_f32_e32 v60, v60
	global_store_dwordx2 v[68:69], v[62:63], off offset:64
	v_and_b32_e32 v62, 0xffff0000, v80
	v_lshlrev_b32_e32 v76, 16, v81
	v_add_f32_e32 v60, 1.0, v60
	v_rcp_f32_e32 v61, v60
	v_mul_f32_e32 v60, 0xbfb8aa3b, v62
	v_exp_f32_e32 v63, v60
	v_mov_b32_e32 v60, v54
	v_pk_mul_f32 v[60:61], v[60:61], v[70:71]
	v_mov_b32_e32 v71, v62
	v_add_f32_e32 v54, 1.0, v63
	global_load_dwordx2 v[62:63], v[58:59], off offset:32
	v_mul_f32_e32 v77, v60, v61
	v_rcp_f32_e32 v61, v54
	v_mul_f32_e32 v54, 0xbfb8aa3b, v76
	v_exp_f32_e32 v79, v54
	v_mov_b32_e32 v60, v55
	v_pk_mul_f32 v[54:55], v[60:61], v[70:71]
	v_and_b32_e32 v78, 0xffff0000, v81
	v_mul_f32_e32 v54, v54, v55
	v_add_f32_e32 v55, 1.0, v79
	v_rcp_f32_e32 v61, v55
	v_mul_f32_e32 v55, 0xbfb8aa3b, v78
	v_mov_b32_e32 v60, v56
	v_exp_f32_e32 v55, v55
	ds_bpermute_b32 v56, v72, v88
	v_cvt_pk_bf16_f32 v54, v77, v54
	v_mov_b32_e32 v71, v76
	v_add_f32_e32 v55, 1.0, v55
	v_rcp_f32_e32 v77, v55
	s_waitcnt lgkmcnt(0)
	v_add_f32_e32 v55, v88, v56
	ds_bpermute_b32 v79, v73, v55
	v_pk_mul_f32 v[60:61], v[60:61], v[70:71]
	v_mov_b32_e32 v76, v57
	v_mul_f32_e32 v60, v60, v61
	v_mov_b32_e32 v71, v78
	s_waitcnt lgkmcnt(0)
	v_add_f32_e32 v61, v55, v79
	v_pk_mul_f32 v[56:57], v[76:77], v[70:71]
	v_div_scale_f32 v70, s[4:5], v61, v61, 1.0
	v_rcp_f32_e32 v71, v70
	v_mul_f32_e32 v55, v56, v57
	v_cvt_pk_bf16_f32 v55, v60, v55
	global_store_dwordx2 v[68:69], v[54:55], off offset:96
	v_fma_f32 v54, -v70, v71, 1.0
	v_fmac_f32_e32 v71, v54, v71
	v_div_scale_f32 v54, vcc, 1.0, v61, 1.0
	v_mul_f32_e32 v55, v54, v71
	v_fma_f32 v56, -v70, v55, v54
	v_fmac_f32_e32 v55, v56, v71
	global_load_dwordx2 v[56:57], v[58:59], off offset:64
	v_fma_f32 v54, -v70, v55, v54
	v_div_fmas_f32 v54, v54, v71, v55
	v_div_fixup_f32 v54, v54, v61, 1.0
	global_load_dwordx2 v[60:61], v[58:59], off offset:96
	s_waitcnt vmcnt(5)
	v_lshlrev_b32_e32 v55, 16, v64
	v_mul_f32_e32 v68, 0xbfb8aa3b, v55
	v_exp_f32_e32 v68, v68
	v_and_b32_e32 v69, 0xffff0000, v64
	v_lshlrev_b32_e32 v70, 16, v65
	v_and_b32_e32 v71, 0xffff0000, v65
	v_add_f32_e32 v64, 1.0, v68
	v_rcp_f32_e32 v65, v64
	v_mul_f32_e32 v64, 0xbfb8aa3b, v69
	v_exp_f32_e32 v68, v64
	v_mov_b32_e32 v64, v46
	v_pk_mul_f32 v[64:65], v[64:65], v[54:55]
	v_mov_b32_e32 v55, v69
	v_add_f32_e32 v46, 1.0, v68
	v_mul_f32_e32 v76, v64, v65
	v_rcp_f32_e32 v65, v46
	v_mul_f32_e32 v46, 0xbfb8aa3b, v70
	v_exp_f32_e32 v68, v46
	v_mov_b32_e32 v64, v47
	v_pk_mul_f32 v[46:47], v[64:65], v[54:55]
	v_mov_b32_e32 v64, v48
	v_mul_f32_e32 v46, v46, v47
	v_add_f32_e32 v47, 1.0, v68
	v_rcp_f32_e32 v65, v47
	v_mul_f32_e32 v47, 0xbfb8aa3b, v71
	v_exp_f32_e32 v47, v47
	v_mov_b32_e32 v55, v70
	v_pk_mul_f32 v[64:65], v[64:65], v[54:55]
	v_mov_b32_e32 v68, v49
	v_add_f32_e32 v47, 1.0, v47
	v_rcp_f32_e32 v69, v47
	v_mov_b32_e32 v55, v71
	v_cvt_pk_bf16_f32 v46, v76, v46
	v_mul_f32_e32 v47, v64, v65
	v_pk_mul_f32 v[48:49], v[68:69], v[54:55]
	s_waitcnt vmcnt(3)
	v_lshlrev_b32_e32 v55, 16, v62
	v_mul_f32_e32 v48, v48, v49
	v_cvt_pk_bf16_f32 v47, v47, v48
	global_store_dwordx2 v[58:59], v[46:47], off
	v_mul_f32_e32 v46, 0xbfb8aa3b, v55
	v_exp_f32_e32 v46, v46
	v_and_b32_e32 v48, 0xffff0000, v62
	v_lshlrev_b32_e32 v62, 16, v63
	v_and_b32_e32 v63, 0xffff0000, v63
	v_add_f32_e32 v46, 1.0, v46
	v_rcp_f32_e32 v47, v46
	v_mul_f32_e32 v46, 0xbfb8aa3b, v48
	v_exp_f32_e32 v49, v46
	v_mov_b32_e32 v46, v50
	v_pk_mul_f32 v[46:47], v[46:47], v[54:55]
	v_mov_b32_e32 v55, v48
	v_mul_f32_e32 v50, v46, v47
	v_add_f32_e32 v46, 1.0, v49
	v_rcp_f32_e32 v47, v46
	v_mul_f32_e32 v48, 0xbfb8aa3b, v62
	v_exp_f32_e32 v48, v48
	v_mov_b32_e32 v46, v51
	v_pk_mul_f32 v[46:47], v[46:47], v[54:55]
	v_mov_b32_e32 v55, v62
	v_mul_f32_e32 v46, v46, v47
	v_add_f32_e32 v47, 1.0, v48
	v_rcp_f32_e32 v49, v47
	v_mul_f32_e32 v47, 0xbfb8aa3b, v63
	v_exp_f32_e32 v47, v47
	v_mov_b32_e32 v48, v52
	v_cvt_pk_bf16_f32 v46, v50, v46
	v_pk_mul_f32 v[48:49], v[48:49], v[54:55]
	v_add_f32_e32 v47, 1.0, v47
	v_rcp_f32_e32 v51, v47
	v_mov_b32_e32 v50, v53
	v_mov_b32_e32 v55, v63
	v_mul_f32_e32 v47, v48, v49
	v_pk_mul_f32 v[48:49], v[50:51], v[54:55]
	v_mfma_f32_16x16x32_bf16 v[42:45], v[98:101], v[38:41], v[212:215]
	v_mul_f32_e32 v48, v48, v49
	s_waitcnt vmcnt(2)
	v_lshlrev_b32_e32 v55, 16, v56
	v_cvt_pk_bf16_f32 v47, v47, v48
	global_store_dwordx2 v[58:59], v[46:47], off offset:32
	v_mul_f32_e32 v46, 0xbfb8aa3b, v55
	v_exp_f32_e32 v46, v46
	v_and_b32_e32 v48, 0xffff0000, v56
	v_lshlrev_b32_e32 v52, 16, v57
	v_mul_f32_e32 v51, 0xbfb8aa3b, v52
	v_add_f32_e32 v46, 1.0, v46
	v_rcp_f32_e32 v47, v46
	v_mul_f32_e32 v46, 0xbfb8aa3b, v48
	v_exp_f32_e32 v49, v46
	v_mov_b32_e32 v46, v42
	v_pk_mul_f32 v[46:47], v[46:47], v[54:55]
	v_mov_b32_e32 v55, v48
	v_add_f32_e32 v42, 1.0, v49
	v_mul_f32_e32 v50, v46, v47
	v_rcp_f32_e32 v47, v42
	v_mov_b32_e32 v46, v43
	v_lshl_add_u64 v[42:43], v[66:67], 0, v[132:133]
	global_load_dwordx2 v[48:49], v[42:43], off
	v_exp_f32_e32 v51, v51
	v_pk_mul_f32 v[46:47], v[46:47], v[54:55]
	v_and_b32_e32 v56, 0xffff0000, v57
	v_mul_f32_e32 v46, v46, v47
	v_add_f32_e32 v47, 1.0, v51
	v_rcp_f32_e32 v51, v47
	v_mul_f32_e32 v47, 0xbfb8aa3b, v56
	v_exp_f32_e32 v47, v47
	v_cvt_pk_bf16_f32 v46, v50, v46
	v_mov_b32_e32 v50, v44
	v_mov_b32_e32 v55, v52
	v_add_f32_e32 v44, 1.0, v47
	v_rcp_f32_e32 v53, v44
	v_pk_mul_f32 v[50:51], v[50:51], v[54:55]
	v_mov_b32_e32 v52, v45
	v_mov_b32_e32 v55, v56
	v_pk_mul_f32 v[44:45], v[52:53], v[54:55]
	v_mul_f32_e32 v47, v50, v51
	v_mul_f32_e32 v44, v44, v45
	s_waitcnt vmcnt(3)
	v_lshlrev_b32_e32 v55, 16, v60
	v_cvt_pk_bf16_f32 v47, v47, v44
	v_mul_f32_e32 v44, 0xbfb8aa3b, v55
	v_exp_f32_e32 v44, v44
	global_store_dwordx2 v[58:59], v[46:47], off offset:64
	v_and_b32_e32 v46, 0xffff0000, v60
	v_mfma_f32_16x16x32_bf16 v[38:41], v[18:21], v[38:41], v[106:109]
	v_add_f32_e32 v44, 1.0, v44
	v_rcp_f32_e32 v45, v44
	v_mul_f32_e32 v44, 0xbfb8aa3b, v46
	v_exp_f32_e32 v47, v44
	v_lshlrev_b32_e32 v50, 16, v61
	s_nop 2
	v_mov_b32_e32 v44, v38
	v_pk_mul_f32 v[44:45], v[44:45], v[54:55]
	v_add_f32_e32 v38, 1.0, v47
	v_mov_b32_e32 v55, v46
	global_load_dwordx2 v[46:47], v[42:43], off offset:32
	v_mul_f32_e32 v51, v44, v45
	v_rcp_f32_e32 v45, v38
	v_mul_f32_e32 v38, 0xbfb8aa3b, v50
	v_exp_f32_e32 v53, v38
	v_mov_b32_e32 v44, v39
	v_pk_mul_f32 v[38:39], v[44:45], v[54:55]
	v_and_b32_e32 v52, 0xffff0000, v61
	v_mul_f32_e32 v38, v38, v39
	v_add_f32_e32 v39, 1.0, v53
	v_rcp_f32_e32 v45, v39
	v_mul_f32_e32 v39, 0xbfb8aa3b, v52
	v_mov_b32_e32 v44, v40
	v_exp_f32_e32 v39, v39
	ds_bpermute_b32 v40, v72, v75
	v_cvt_pk_bf16_f32 v38, v51, v38
	v_mov_b32_e32 v55, v50
	v_add_f32_e32 v39, 1.0, v39
	v_rcp_f32_e32 v51, v39
	s_waitcnt lgkmcnt(0)
	v_add_f32_e32 v39, v75, v40
	ds_bpermute_b32 v53, v73, v39
	v_pk_mul_f32 v[44:45], v[44:45], v[54:55]
	v_mov_b32_e32 v50, v41
	v_mul_f32_e32 v44, v44, v45
	v_mov_b32_e32 v55, v52
	s_waitcnt lgkmcnt(0)
	v_add_f32_e32 v45, v39, v53
	v_pk_mul_f32 v[40:41], v[50:51], v[54:55]
	v_div_scale_f32 v50, s[4:5], v45, v45, 1.0
	v_rcp_f32_e32 v51, v50
	v_mul_f32_e32 v39, v40, v41
	v_cvt_pk_bf16_f32 v39, v44, v39
	global_store_dwordx2 v[58:59], v[38:39], off offset:96
	v_fma_f32 v38, -v50, v51, 1.0
	v_fmac_f32_e32 v51, v38, v51
	v_div_scale_f32 v38, vcc, 1.0, v45, 1.0
	v_mul_f32_e32 v39, v38, v51
	v_fma_f32 v40, -v50, v39, v38
	v_fmac_f32_e32 v39, v40, v51
	global_load_dwordx2 v[40:41], v[42:43], off offset:64
	v_fma_f32 v38, -v50, v39, v38
	v_div_fmas_f32 v38, v38, v51, v39
	v_div_fixup_f32 v38, v38, v45, 1.0
	global_load_dwordx2 v[44:45], v[42:43], off offset:96
	s_waitcnt vmcnt(5)
	v_lshlrev_b32_e32 v39, 16, v48
	v_mul_f32_e32 v50, 0xbfb8aa3b, v39
	v_exp_f32_e32 v50, v50
	v_and_b32_e32 v51, 0xffff0000, v48
	v_lshlrev_b32_e32 v52, 16, v49
	v_and_b32_e32 v53, 0xffff0000, v49
	v_add_f32_e32 v48, 1.0, v50
	v_rcp_f32_e32 v49, v48
	v_mul_f32_e32 v48, 0xbfb8aa3b, v51
	v_exp_f32_e32 v50, v48
	v_mov_b32_e32 v48, v30
	v_pk_mul_f32 v[48:49], v[48:49], v[38:39]
	v_mov_b32_e32 v39, v51
	v_add_f32_e32 v30, 1.0, v50
	v_mul_f32_e32 v54, v48, v49
	v_rcp_f32_e32 v49, v30
	v_mul_f32_e32 v30, 0xbfb8aa3b, v52
	v_exp_f32_e32 v50, v30
	v_mov_b32_e32 v48, v31
	v_pk_mul_f32 v[30:31], v[48:49], v[38:39]
	v_mov_b32_e32 v48, v32
	v_mul_f32_e32 v30, v30, v31
	v_add_f32_e32 v31, 1.0, v50
	v_rcp_f32_e32 v49, v31
	v_mul_f32_e32 v31, 0xbfb8aa3b, v53
	v_exp_f32_e32 v31, v31
	v_mov_b32_e32 v39, v52
	v_pk_mul_f32 v[48:49], v[48:49], v[38:39]
	v_mov_b32_e32 v50, v33
	v_add_f32_e32 v31, 1.0, v31
	v_rcp_f32_e32 v51, v31
	v_mov_b32_e32 v39, v53
	v_cvt_pk_bf16_f32 v30, v54, v30
	v_mul_f32_e32 v31, v48, v49
	v_pk_mul_f32 v[32:33], v[50:51], v[38:39]
	s_waitcnt vmcnt(3)
	v_lshlrev_b32_e32 v39, 16, v46
	v_mul_f32_e32 v32, v32, v33
	v_cvt_pk_bf16_f32 v31, v31, v32
	global_store_dwordx2 v[42:43], v[30:31], off
	v_mul_f32_e32 v30, 0xbfb8aa3b, v39
	v_exp_f32_e32 v30, v30
	v_and_b32_e32 v32, 0xffff0000, v46
	v_lshlrev_b32_e32 v46, 16, v47
	v_and_b32_e32 v47, 0xffff0000, v47
	v_add_f32_e32 v30, 1.0, v30
	v_rcp_f32_e32 v31, v30
	v_mul_f32_e32 v30, 0xbfb8aa3b, v32
	v_exp_f32_e32 v33, v30
	v_mov_b32_e32 v30, v34
	v_pk_mul_f32 v[30:31], v[30:31], v[38:39]
	v_mov_b32_e32 v39, v32
	v_mul_f32_e32 v34, v30, v31
	v_add_f32_e32 v30, 1.0, v33
	v_rcp_f32_e32 v31, v30
	v_mul_f32_e32 v32, 0xbfb8aa3b, v46
	v_exp_f32_e32 v32, v32
	v_mov_b32_e32 v30, v35
	v_pk_mul_f32 v[30:31], v[30:31], v[38:39]
	v_mov_b32_e32 v39, v46
	v_mul_f32_e32 v30, v30, v31
	v_add_f32_e32 v31, 1.0, v32
	v_rcp_f32_e32 v33, v31
	v_mul_f32_e32 v31, 0xbfb8aa3b, v47
	v_exp_f32_e32 v31, v31
	v_mov_b32_e32 v32, v36
	v_cvt_pk_bf16_f32 v30, v34, v30
	v_pk_mul_f32 v[32:33], v[32:33], v[38:39]
	v_add_f32_e32 v31, 1.0, v31
	v_rcp_f32_e32 v35, v31
	v_mov_b32_e32 v34, v37
	v_mov_b32_e32 v39, v47
	v_mul_f32_e32 v31, v32, v33
	v_pk_mul_f32 v[32:33], v[34:35], v[38:39]
	v_mfma_f32_16x16x32_bf16 v[26:29], v[98:101], v[148:151], v[216:219]
	v_mul_f32_e32 v32, v32, v33
	s_waitcnt vmcnt(2)
	v_lshlrev_b32_e32 v39, 16, v40
	v_cvt_pk_bf16_f32 v31, v31, v32
	global_store_dwordx2 v[42:43], v[30:31], off offset:32
	v_mul_f32_e32 v30, 0xbfb8aa3b, v39
	v_exp_f32_e32 v30, v30
	v_and_b32_e32 v32, 0xffff0000, v40
	v_lshlrev_b32_e32 v36, 16, v41
	v_mul_f32_e32 v35, 0xbfb8aa3b, v36
	v_add_f32_e32 v30, 1.0, v30
	v_rcp_f32_e32 v31, v30
	v_mul_f32_e32 v30, 0xbfb8aa3b, v32
	v_exp_f32_e32 v33, v30
	v_mov_b32_e32 v30, v26
	v_pk_mul_f32 v[30:31], v[30:31], v[38:39]
	v_mov_b32_e32 v39, v32
	v_add_f32_e32 v26, 1.0, v33
	v_mul_f32_e32 v34, v30, v31
	v_rcp_f32_e32 v31, v26
	v_mov_b32_e32 v30, v27
	v_lshl_add_u64 v[26:27], v[66:67], 0, v[130:131]
	global_load_dwordx2 v[32:33], v[26:27], off
	v_exp_f32_e32 v35, v35
	v_pk_mul_f32 v[30:31], v[30:31], v[38:39]
	v_and_b32_e32 v40, 0xffff0000, v41
	v_mul_f32_e32 v30, v30, v31
	v_add_f32_e32 v31, 1.0, v35
	v_rcp_f32_e32 v35, v31
	v_mul_f32_e32 v31, 0xbfb8aa3b, v40
	v_exp_f32_e32 v31, v31
	v_cvt_pk_bf16_f32 v30, v34, v30
	v_mov_b32_e32 v34, v28
	v_mov_b32_e32 v39, v36
	v_add_f32_e32 v28, 1.0, v31
	v_rcp_f32_e32 v37, v28
	v_pk_mul_f32 v[34:35], v[34:35], v[38:39]
	v_mov_b32_e32 v36, v29
	v_mov_b32_e32 v39, v40
	v_pk_mul_f32 v[28:29], v[36:37], v[38:39]
	v_mul_f32_e32 v31, v34, v35
	v_mul_f32_e32 v28, v28, v29
	s_waitcnt vmcnt(3)
	v_lshlrev_b32_e32 v39, 16, v44
	v_cvt_pk_bf16_f32 v31, v31, v28
	v_mul_f32_e32 v28, 0xbfb8aa3b, v39
	v_exp_f32_e32 v28, v28
	global_store_dwordx2 v[42:43], v[30:31], off offset:64
	v_and_b32_e32 v30, 0xffff0000, v44
	v_mfma_f32_16x16x32_bf16 v[22:25], v[18:21], v[148:151], v[110:113]
	v_add_f32_e32 v28, 1.0, v28
	v_rcp_f32_e32 v29, v28
	v_mul_f32_e32 v28, 0xbfb8aa3b, v30
	v_exp_f32_e32 v31, v28
	v_lshlrev_b32_e32 v34, 16, v45
	s_nop 2
	v_mov_b32_e32 v28, v22
	v_pk_mul_f32 v[28:29], v[28:29], v[38:39]
	v_add_f32_e32 v22, 1.0, v31
	v_mul_f32_e32 v35, v28, v29
	v_rcp_f32_e32 v29, v22
	v_mov_b32_e32 v28, v23
	global_load_dwordx2 v[22:23], v[26:27], off offset:32
	v_mov_b32_e32 v39, v30
	v_mul_f32_e32 v30, 0xbfb8aa3b, v34
	v_exp_f32_e32 v30, v30
	v_pk_mul_f32 v[28:29], v[28:29], v[38:39]
	v_and_b32_e32 v36, 0xffff0000, v45
	v_mul_f32_e32 v28, v28, v29
	v_add_f32_e32 v29, 1.0, v30
	v_rcp_f32_e32 v31, v29
	ds_bpermute_b32 v29, v72, v74
	v_mov_b32_e32 v30, v24
	v_mul_f32_e32 v24, 0xbfb8aa3b, v36
	v_exp_f32_e32 v24, v24
	v_cvt_pk_bf16_f32 v28, v35, v28
	s_waitcnt lgkmcnt(0)
	v_add_f32_e32 v29, v74, v29
	ds_bpermute_b32 v37, v73, v29
	v_add_f32_e32 v24, 1.0, v24
	v_rcp_f32_e32 v35, v24
	v_mov_b32_e32 v39, v34
	v_pk_mul_f32 v[30:31], v[30:31], v[38:39]
	v_mov_b32_e32 v34, v25
	v_mul_f32_e32 v30, v30, v31
	v_mov_b32_e32 v39, v36
	s_waitcnt lgkmcnt(0)
	v_add_f32_e32 v31, v29, v37
	v_pk_mul_f32 v[24:25], v[34:35], v[38:39]
	v_div_scale_f32 v34, s[4:5], v31, v31, 1.0
	v_rcp_f32_e32 v35, v34
	v_mul_f32_e32 v24, v24, v25
	v_cvt_pk_bf16_f32 v29, v30, v24
	global_store_dwordx2 v[42:43], v[28:29], off offset:96
	v_fma_f32 v24, -v34, v35, 1.0
	v_fmac_f32_e32 v35, v24, v35
	v_div_scale_f32 v24, vcc, 1.0, v31, 1.0
	v_mul_f32_e32 v28, v24, v35
	v_fma_f32 v25, -v34, v28, v24
	v_fmac_f32_e32 v28, v25, v35
	v_fma_f32 v29, -v34, v28, v24
	global_load_dwordx2 v[24:25], v[26:27], off offset:64
	v_div_fmas_f32 v28, v29, v35, v28
	v_div_fixup_f32 v28, v28, v31, 1.0
	global_load_dwordx2 v[30:31], v[26:27], off offset:96
	s_waitcnt vmcnt(5)
	v_lshlrev_b32_e32 v29, 16, v32
	v_mul_f32_e32 v34, 0xbfb8aa3b, v29
	v_exp_f32_e32 v34, v34
	v_and_b32_e32 v35, 0xffff0000, v32
	v_lshlrev_b32_e32 v36, 16, v33
	v_and_b32_e32 v37, 0xffff0000, v33
	v_add_f32_e32 v32, 1.0, v34
	v_rcp_f32_e32 v33, v32
	v_mul_f32_e32 v32, 0xbfb8aa3b, v35
	v_exp_f32_e32 v34, v32
	v_mov_b32_e32 v32, v4
	v_pk_mul_f32 v[32:33], v[32:33], v[28:29]
	v_mov_b32_e32 v29, v35
	v_add_f32_e32 v4, 1.0, v34
	v_mul_f32_e32 v38, v32, v33
	v_rcp_f32_e32 v33, v4
	v_mul_f32_e32 v4, 0xbfb8aa3b, v36
	v_exp_f32_e32 v34, v4
	v_mov_b32_e32 v32, v5
	v_pk_mul_f32 v[4:5], v[32:33], v[28:29]
	v_mov_b32_e32 v32, v6
	v_mul_f32_e32 v4, v4, v5
	v_add_f32_e32 v5, 1.0, v34
	v_rcp_f32_e32 v33, v5
	v_mul_f32_e32 v5, 0xbfb8aa3b, v37
	v_exp_f32_e32 v5, v5
	v_mov_b32_e32 v29, v36
	v_pk_mul_f32 v[32:33], v[32:33], v[28:29]
	v_mov_b32_e32 v34, v7
	v_add_f32_e32 v5, 1.0, v5
	v_rcp_f32_e32 v35, v5
	v_mov_b32_e32 v29, v37
	v_cvt_pk_bf16_f32 v4, v38, v4
	v_mul_f32_e32 v5, v32, v33
	v_pk_mul_f32 v[6:7], v[34:35], v[28:29]
	v_mfma_f32_16x16x32_bf16 v[18:21], v[18:21], v[152:155], v[114:117]
	v_mul_f32_e32 v6, v6, v7
	s_waitcnt vmcnt(3)
	v_lshlrev_b32_e32 v29, 16, v22
	v_cvt_pk_bf16_f32 v5, v5, v6
	global_store_dwordx2 v[26:27], v[4:5], off
	v_mul_f32_e32 v4, 0xbfb8aa3b, v29
	v_exp_f32_e32 v4, v4
	v_and_b32_e32 v6, 0xffff0000, v22
	v_lshlrev_b32_e32 v22, 16, v23
	v_and_b32_e32 v23, 0xffff0000, v23
	v_add_f32_e32 v4, 1.0, v4
	v_rcp_f32_e32 v5, v4
	v_mul_f32_e32 v4, 0xbfb8aa3b, v6
	v_exp_f32_e32 v7, v4
	v_mov_b32_e32 v4, v12
	v_pk_mul_f32 v[4:5], v[4:5], v[28:29]
	v_mov_b32_e32 v29, v6
	v_mul_f32_e32 v12, v4, v5
	v_add_f32_e32 v4, 1.0, v7
	v_rcp_f32_e32 v5, v4
	v_mul_f32_e32 v6, 0xbfb8aa3b, v22
	v_exp_f32_e32 v6, v6
	v_mov_b32_e32 v4, v13
	v_pk_mul_f32 v[4:5], v[4:5], v[28:29]
	v_mov_b32_e32 v29, v22
	v_mul_f32_e32 v4, v4, v5
	v_add_f32_e32 v5, 1.0, v6
	v_rcp_f32_e32 v7, v5
	v_mul_f32_e32 v5, 0xbfb8aa3b, v23
	v_exp_f32_e32 v5, v5
	v_mov_b32_e32 v6, v14
	v_cvt_pk_bf16_f32 v4, v12, v4
	v_pk_mul_f32 v[6:7], v[6:7], v[28:29]
	v_add_f32_e32 v5, 1.0, v5
	v_rcp_f32_e32 v13, v5
	v_mov_b32_e32 v12, v15
	v_mov_b32_e32 v29, v23
	v_mul_f32_e32 v5, v6, v7
	v_pk_mul_f32 v[6:7], v[12:13], v[28:29]
	s_waitcnt vmcnt(2)
	v_lshlrev_b32_e32 v29, 16, v24
	v_mul_f32_e32 v6, v6, v7
	v_cvt_pk_bf16_f32 v5, v5, v6
	global_store_dwordx2 v[26:27], v[4:5], off offset:32
	v_mul_f32_e32 v4, 0xbfb8aa3b, v29
	v_exp_f32_e32 v4, v4
	v_and_b32_e32 v6, 0xffff0000, v24
	v_lshlrev_b32_e32 v12, 16, v25
	v_and_b32_e32 v13, 0xffff0000, v25
	v_add_f32_e32 v4, 1.0, v4
	v_rcp_f32_e32 v5, v4
	v_mul_f32_e32 v4, 0xbfb8aa3b, v6
	v_exp_f32_e32 v7, v4
	v_mov_b32_e32 v4, v8
	v_pk_mul_f32 v[4:5], v[4:5], v[28:29]
	v_mov_b32_e32 v29, v6
	v_mul_f32_e32 v8, v4, v5
	v_add_f32_e32 v4, 1.0, v7
	v_rcp_f32_e32 v5, v4
	v_mul_f32_e32 v6, 0xbfb8aa3b, v12
	v_exp_f32_e32 v6, v6
	v_mov_b32_e32 v4, v9
	v_pk_mul_f32 v[4:5], v[4:5], v[28:29]
	v_mov_b32_e32 v29, v12
	v_mul_f32_e32 v4, v4, v5
	v_add_f32_e32 v5, 1.0, v6
	v_rcp_f32_e32 v7, v5
	v_mul_f32_e32 v5, 0xbfb8aa3b, v13
	v_exp_f32_e32 v5, v5
	v_mov_b32_e32 v6, v10
	v_cvt_pk_bf16_f32 v4, v8, v4
	v_pk_mul_f32 v[6:7], v[6:7], v[28:29]
	v_add_f32_e32 v5, 1.0, v5
	v_rcp_f32_e32 v9, v5
	v_mov_b32_e32 v8, v11
	v_mov_b32_e32 v29, v13
	v_mul_f32_e32 v5, v6, v7
	v_pk_mul_f32 v[6:7], v[8:9], v[28:29]
	s_waitcnt vmcnt(2)
	v_lshlrev_b32_e32 v29, 16, v30
	v_mul_f32_e32 v6, v6, v7
	v_cvt_pk_bf16_f32 v5, v5, v6
	global_store_dwordx2 v[26:27], v[4:5], off offset:64
	v_mul_f32_e32 v4, 0xbfb8aa3b, v29
	v_exp_f32_e32 v4, v4
	v_and_b32_e32 v6, 0xffff0000, v30
	v_lshlrev_b32_e32 v8, 16, v31
	v_and_b32_e32 v10, 0xffff0000, v31
	v_add_f32_e32 v4, 1.0, v4
	v_rcp_f32_e32 v5, v4
	v_mul_f32_e32 v4, 0xbfb8aa3b, v6
	v_exp_f32_e32 v7, v4
	v_mov_b32_e32 v4, v18
	v_pk_mul_f32 v[4:5], v[4:5], v[28:29]
	v_mov_b32_e32 v29, v6
	v_mul_f32_e32 v9, v4, v5
	v_add_f32_e32 v4, 1.0, v7
	v_rcp_f32_e32 v5, v4
	v_mul_f32_e32 v6, 0xbfb8aa3b, v8
	v_exp_f32_e32 v6, v6
	v_mov_b32_e32 v4, v19
	v_pk_mul_f32 v[4:5], v[4:5], v[28:29]
	v_mov_b32_e32 v29, v8
	v_mul_f32_e32 v4, v4, v5
	v_add_f32_e32 v5, 1.0, v6
	v_rcp_f32_e32 v7, v5
	v_mul_f32_e32 v5, 0xbfb8aa3b, v10
	v_exp_f32_e32 v5, v5
	v_cvt_pk_bf16_f32 v4, v9, v4
	v_mov_b32_e32 v6, v20
	v_pk_mul_f32 v[6:7], v[6:7], v[28:29]
	v_add_f32_e32 v5, 1.0, v5
	v_rcp_f32_e32 v9, v5
	v_mov_b32_e32 v8, v21
	v_mov_b32_e32 v29, v10
	v_mul_f32_e32 v5, v6, v7
	v_pk_mul_f32 v[6:7], v[8:9], v[28:29]
	s_nop 0
	v_mul_f32_e32 v6, v6, v7
	v_cvt_pk_bf16_f32 v5, v5, v6
	global_store_dwordx2 v[26:27], v[4:5], off offset:96
	s_cbranch_scc0 .LBB0_937
